# k41 + hand-written EpiPle (P8): packed f32 math, rolling window of 16 outstanding loads with counted vmcnt waits
# baseline (speedup 1.0000x reference)
; __device__ __forceinline__ void row_rs8(const float* SS, int row0, int fq, float (&rsv)[2][4]) {
;     f32x4 q[2][4];
; #pragma unroll
;     for (int ai = 0; ai < 2; ++ai)
; #pragma unroll
;         for (int m = 0; m < 4; ++m) q[ai][m] = *(const f32x4*)(SS + (size_t)(row0 + ai * HALF + m * 16) * 16 + 4 * fq);
; #pragma unroll
;     for (int ai = 0; ai < 2; ++ai)
; #pragma unroll
;         for (int m = 0; m < 4; ++m) { float t = (q[ai][m][0] + q[ai][m][1]) + (q[ai][m][2] + q[ai][m][3]); t += __shfl_xor(t, 16); t += __shfl_xor(t, 32); rsv[ai][m] = __builtin_amdgcn_rsqf(t * (1.0f / 1024.0f) + 1e-6f); }
; }
;     __device__ __forceinline__ void operator()(const f32x4 (&acc)[2][2][4][2], const Unit& u, int wr, int wc, int fr, int fq) const {
;         const int row0 = u.pm * BM + wr * 64 + fr, col0 = u.pn * BM + wc * 32 + 8 * fq;
;         float rsv[2][4]; row_rs8(SS, row0, fq, rsv);
; #pragma unroll
;         for (int ai = 0; ai < 2; ++ai)
; #pragma unroll
;             for (int mp = 0; mp < 2; ++mp) {
;                 u32x4 xr[2][2], pr[2][2];
; #pragma unroll
;                 for (int mm = 0; mm < 2; ++mm)
; #pragma unroll
;                     for (int bj = 0; bj < 2; ++bj) { const size_t off = (size_t)(row0 + ai * HALF + (2 * mp + mm) * 16) * 1024 + col0 + bj * HALF; xr[mm][bj] = *(const u32x4*)(XB + off); pr[mm][bj] = *(const u32x4*)(P + off); }
; #pragma unroll
;                 for (int mm = 0; mm < 2; ++mm) {
;                     const int m = 2 * mp + mm; const int r = row0 + ai * HALF + m * 16; const float nrs = rsv[ai][m] * -1.4426950408889634f;
; #pragma unroll
;                     for (int bj = 0; bj < 2; ++bj) {
;                         const size_t off = (size_t)r * 1024 + col0 + bj * HALF;
;                         const unsigned xw[4] = {xr[mm][bj].x, xr[mm][bj].y, xr[mm][bj].z, xr[mm][bj].w}, pw[4] = {pr[mm][bj].x, pr[mm][bj].y, pr[mm][bj].z, pr[mm][bj].w};
;                         f32x4 o[2];
; #pragma unroll
;                         for (int q = 0; q < 4; ++q) {
;                             const float t0 = acc[ai][bj][m][q >> 1][2 * (q & 1)] * nrs, t1 = acc[ai][bj][m][q >> 1][2 * (q & 1) + 1] * nrs;
;                             o[q >> 1][2 * (q & 1)] = __uint_as_float(xw[q] << 16) + fast_rcp(1.0f + __builtin_amdgcn_exp2f(t0)) * __uint_as_float(pw[q] << 16);
.LBB0_1256:
	v_lshl_add_u32 v219, s51, 8, v193
	v_or_b32_e32 v228, 16, v219
	v_or_b32_e32 v229, 32, v219
	v_or_b32_e32 v230, 48, v219
	v_add_u32_e32 v231, 0x80, v219
	v_add_u32_e32 v232, 0x90, v219
	v_add_u32_e32 v233, 0xa0, v219
	v_add_u32_e32 v234, 0xb0, v219
	v_mov_b32_e32 v227, 0
	v_lshlrev_b32_e32 v226, 6, v219
	v_lshl_add_u64 v[220:221], v[184:185], 0, v[226:227]
	global_load_dwordx4 v[124:127], v[220:221], off
	v_lshlrev_b32_e32 v226, 6, v228
	v_lshl_add_u64 v[220:221], v[184:185], 0, v[226:227]
	global_load_dwordx4 v[132:135], v[220:221], off
	v_lshlrev_b32_e32 v226, 6, v229
	v_lshl_add_u64 v[220:221], v[184:185], 0, v[226:227]
	global_load_dwordx4 v[136:139], v[220:221], off
	v_lshlrev_b32_e32 v226, 6, v230
	v_lshl_add_u64 v[220:221], v[184:185], 0, v[226:227]
	global_load_dwordx4 v[140:143], v[220:221], off
	v_lshlrev_b32_e32 v226, 6, v231
	v_lshl_add_u64 v[220:221], v[184:185], 0, v[226:227]
	global_load_dwordx4 v[144:147], v[220:221], off
	v_lshlrev_b32_e32 v226, 6, v232
	v_lshl_add_u64 v[220:221], v[184:185], 0, v[226:227]
	global_load_dwordx4 v[148:151], v[220:221], off
	v_lshlrev_b32_e32 v226, 6, v233
	v_lshl_add_u64 v[220:221], v[184:185], 0, v[226:227]
	global_load_dwordx4 v[152:155], v[220:221], off
	v_lshlrev_b32_e32 v226, 6, v234
	v_lshl_add_u64 v[220:221], v[184:185], 0, v[226:227]
	global_load_dwordx4 v[156:159], v[220:221], off
	v_lshl_or_b32 v246, s52, 8, v213
	v_lshlrev_b32_e32 v246, 1, v246
	v_lshl_add_u32 v219, v219, 11, v246
	v_lshl_add_u32 v228, v228, 11, v246
	v_lshl_add_u32 v229, v229, 11, v246
	v_lshl_add_u32 v230, v230, 11, v246
	v_lshl_add_u32 v231, v231, 11, v246
	v_lshl_add_u32 v232, v232, 11, v246
	v_lshl_add_u32 v233, v233, 11, v246
	v_lshl_add_u32 v234, v234, 11, v246
	v_xor_b32_e32 v243, 16, v217
	v_xor_b32_e32 v244, 32, v217
	v_lshlrev_b32_e32 v243, 2, v243
	v_lshlrev_b32_e32 v244, 2, v244
	global_load_dwordx4 v[160:163], v219, s[34:35]
	global_load_dwordx4 v[164:167], v219, s[46:47]
	global_load_dwordx4 v[168:171], v219, s[34:35] offset:256
	global_load_dwordx4 v[172:175], v219, s[46:47] offset:256
	global_load_dwordx4 v[196:199], v228, s[34:35]
	global_load_dwordx4 v[200:203], v228, s[46:47]
	global_load_dwordx4 v[204:207], v228, s[34:35] offset:256
	global_load_dwordx4 v[208:211], v228, s[46:47] offset:256
	s_waitcnt vmcnt(8)
	v_pk_add_f32 v[124:125], v[124:125], v[126:127]
	v_pk_add_f32 v[132:133], v[132:133], v[134:135]
	v_pk_add_f32 v[136:137], v[136:137], v[138:139]
	v_pk_add_f32 v[140:141], v[140:141], v[142:143]
	v_pk_add_f32 v[144:145], v[144:145], v[146:147]
	v_pk_add_f32 v[148:149], v[148:149], v[150:151]
	v_pk_add_f32 v[152:153], v[152:153], v[154:155]
	v_pk_add_f32 v[156:157], v[156:157], v[158:159]
	v_add_f32_e32 v235, v124, v125
	v_add_f32_e32 v236, v132, v133
	v_add_f32_e32 v237, v136, v137
	v_add_f32_e32 v238, v140, v141
	v_add_f32_e32 v239, v144, v145
	v_add_f32_e32 v240, v148, v149
	v_add_f32_e32 v241, v152, v153
	v_add_f32_e32 v242, v156, v157
	ds_bpermute_b32 v126, v243, v235
	ds_bpermute_b32 v134, v243, v236
	ds_bpermute_b32 v138, v243, v237
	ds_bpermute_b32 v142, v243, v238
	ds_bpermute_b32 v146, v243, v239
	ds_bpermute_b32 v150, v243, v240
	ds_bpermute_b32 v154, v243, v241
	ds_bpermute_b32 v158, v243, v242
	s_waitcnt lgkmcnt(7)
	v_add_f32_e32 v235, v235, v126
	s_waitcnt lgkmcnt(6)
	v_add_f32_e32 v236, v236, v134
	s_waitcnt lgkmcnt(5)
	v_add_f32_e32 v237, v237, v138
	s_waitcnt lgkmcnt(4)
	v_add_f32_e32 v238, v238, v142
	s_waitcnt lgkmcnt(3)
	v_add_f32_e32 v239, v239, v146
	s_waitcnt lgkmcnt(2)
	v_add_f32_e32 v240, v240, v150
	s_waitcnt lgkmcnt(1)
	v_add_f32_e32 v241, v241, v154
	s_waitcnt lgkmcnt(0)
	v_add_f32_e32 v242, v242, v158
	ds_bpermute_b32 v126, v244, v235
	ds_bpermute_b32 v134, v244, v236
	ds_bpermute_b32 v138, v244, v237
	ds_bpermute_b32 v142, v244, v238
	ds_bpermute_b32 v146, v244, v239
	ds_bpermute_b32 v150, v244, v240
	ds_bpermute_b32 v154, v244, v241
	ds_bpermute_b32 v158, v244, v242
	s_waitcnt lgkmcnt(7)
	v_add_f32_e32 v235, v235, v126
	s_waitcnt lgkmcnt(6)
	v_add_f32_e32 v236, v236, v134
	s_waitcnt lgkmcnt(5)
	v_add_f32_e32 v237, v237, v138
	s_waitcnt lgkmcnt(4)
	v_add_f32_e32 v238, v238, v142
	s_waitcnt lgkmcnt(3)
	v_add_f32_e32 v239, v239, v146
	s_waitcnt lgkmcnt(2)
	v_add_f32_e32 v240, v240, v150
	s_waitcnt lgkmcnt(1)
	v_add_f32_e32 v241, v241, v154
	s_waitcnt lgkmcnt(0)
	v_add_f32_e32 v242, v242, v158
	v_fmamk_f32 v235, v235, 0x3a800000, v218
	v_fmamk_f32 v236, v236, 0x3a800000, v218
	v_fmamk_f32 v237, v237, 0x3a800000, v218
	v_fmamk_f32 v238, v238, 0x3a800000, v218
	v_fmamk_f32 v239, v239, 0x3a800000, v218
	v_fmamk_f32 v240, v240, 0x3a800000, v218
	v_fmamk_f32 v241, v241, 0x3a800000, v218
	v_fmamk_f32 v242, v242, 0x3a800000, v218
	v_rsq_f32_e32 v235, v235
	v_rsq_f32_e32 v236, v236
	v_rsq_f32_e32 v237, v237
	v_rsq_f32_e32 v238, v238
	v_rsq_f32_e32 v239, v239
	v_rsq_f32_e32 v240, v240
	v_rsq_f32_e32 v241, v241
	v_rsq_f32_e32 v242, v242
	global_load_dwordx4 v[124:127], v229, s[34:35]
	global_load_dwordx4 v[132:135], v229, s[46:47]
	global_load_dwordx4 v[136:139], v229, s[34:35] offset:256
	global_load_dwordx4 v[140:143], v229, s[46:47] offset:256
	global_load_dwordx4 v[144:147], v230, s[34:35]
	global_load_dwordx4 v[148:151], v230, s[46:47]
	global_load_dwordx4 v[152:155], v230, s[34:35] offset:256
	global_load_dwordx4 v[156:159], v230, s[46:47] offset:256
	v_mul_f32_e32 v235, 0xbfb8aa3b, v235
	v_mul_f32_e32 v236, 0xbfb8aa3b, v236
	v_mul_f32_e32 v237, 0xbfb8aa3b, v237
	v_mul_f32_e32 v238, 0xbfb8aa3b, v238
	v_mul_f32_e32 v239, 0xbfb8aa3b, v239
	v_mul_f32_e32 v240, 0xbfb8aa3b, v240
	v_mul_f32_e32 v241, 0xbfb8aa3b, v241
	v_mul_f32_e32 v242, 0xbfb8aa3b, v242
	v_mov_b32_e32 v224, v235
	v_pk_mul_f32 v[128:129], v[128:129], v[224:225] op_sel_hi:[1,0]
	v_pk_mul_f32 v[130:131], v[130:131], v[224:225] op_sel_hi:[1,0]
	v_pk_mul_f32 v[120:121], v[120:121], v[224:225] op_sel_hi:[1,0]
	v_pk_mul_f32 v[122:123], v[122:123], v[224:225] op_sel_hi:[1,0]
	v_exp_f32_e32 v128, v128
	v_exp_f32_e32 v129, v129
	v_exp_f32_e32 v130, v130
	v_exp_f32_e32 v131, v131
	v_exp_f32_e32 v120, v120
	v_exp_f32_e32 v121, v121
	v_exp_f32_e32 v122, v122
	v_exp_f32_e32 v123, v123
	v_pk_add_f32 v[128:129], v[128:129], 1.0 op_sel_hi:[1,0]
	v_pk_add_f32 v[130:131], v[130:131], 1.0 op_sel_hi:[1,0]
	v_pk_add_f32 v[120:121], v[120:121], 1.0 op_sel_hi:[1,0]
	v_pk_add_f32 v[122:123], v[122:123], 1.0 op_sel_hi:[1,0]
	v_rcp_f32_e32 v128, v128
	v_rcp_f32_e32 v129, v129
	v_rcp_f32_e32 v130, v130
	v_rcp_f32_e32 v131, v131
	v_rcp_f32_e32 v120, v120
	v_rcp_f32_e32 v121, v121
	v_rcp_f32_e32 v122, v122
	v_rcp_f32_e32 v123, v123
	v_lshlrev_b32_e32 v245, 1, v219
	s_waitcnt vmcnt(14)
; __device__ __forceinline__ float fast_rcp(float x) { return __builtin_amdgcn_rcpf(x); }
;     __device__ __forceinline__ void operator()(const f32x4 (&acc)[2][2][4][2], const Unit& u, int wr, int wc, int fr, int fq) const {
;     ...
;                 for (int mm = 0; mm < 2; ++mm) {
;                     const int m = 2 * mp + mm; const int r = row0 + ai * HALF + m * 16; const float nrs = rsv[ai][m] * -1.4426950408889634f;
; #pragma unroll
;                     for (int bj = 0; bj < 2; ++bj) {
;                         const size_t off = (size_t)r * 1024 + col0 + bj * HALF;
;                         const unsigned xw[4] = {xr[mm][bj].x, xr[mm][bj].y, xr[mm][bj].z, xr[mm][bj].w}, pw[4] = {pr[mm][bj].x, pr[mm][bj].y, pr[mm][bj].z, pr[mm][bj].w};
;                         f32x4 o[2];
; #pragma unroll
;                         for (int q = 0; q < 4; ++q) {
;                             const float t0 = acc[ai][bj][m][q >> 1][2 * (q & 1)] * nrs, t1 = acc[ai][bj][m][q >> 1][2 * (q & 1) + 1] * nrs;
;                             o[q >> 1][2 * (q & 1)] = __uint_as_float(xw[q] << 16) + fast_rcp(1.0f + __builtin_amdgcn_exp2f(t0)) * __uint_as_float(pw[q] << 16);
;                             o[q >> 1][2 * (q & 1) + 1] = __uint_as_float(xw[q] & 0xffff0000u) + fast_rcp(1.0f + __builtin_amdgcn_exp2f(t1)) * __uint_as_float(pw[q] & 0xffff0000u);
;                         }
;                         *(f32x4*)(Y + off) = o[0]; *(f32x4*)(Y + off + 4) = o[1];
	v_lshlrev_b32_e32 v220, 16, v160
	v_and_b32_e32 v221, 0xffff0000, v160
	v_lshlrev_b32_e32 v222, 16, v164
	v_and_b32_e32 v223, 0xffff0000, v164
	v_pk_fma_f32 v[128:129], v[128:129], v[222:223], v[220:221]
	v_lshlrev_b32_e32 v220, 16, v161
	v_and_b32_e32 v221, 0xffff0000, v161
	v_lshlrev_b32_e32 v222, 16, v165
	v_and_b32_e32 v223, 0xffff0000, v165
	v_pk_fma_f32 v[130:131], v[130:131], v[222:223], v[220:221]
	v_lshlrev_b32_e32 v220, 16, v162
	v_and_b32_e32 v221, 0xffff0000, v162
	v_lshlrev_b32_e32 v222, 16, v166
	v_and_b32_e32 v223, 0xffff0000, v166
	v_pk_fma_f32 v[120:121], v[120:121], v[222:223], v[220:221]
	v_lshlrev_b32_e32 v220, 16, v163
	v_and_b32_e32 v221, 0xffff0000, v163
	v_lshlrev_b32_e32 v222, 16, v167
	v_and_b32_e32 v223, 0xffff0000, v167
	v_pk_fma_f32 v[122:123], v[122:123], v[222:223], v[220:221]
	global_store_dwordx4 v245, v[128:131], s[24:25]
	global_store_dwordx4 v245, v[120:123], s[24:25] offset:16
	global_load_dwordx4 v[160:163], v231, s[34:35]
	global_load_dwordx4 v[164:167], v231, s[46:47]
	v_mov_b32_e32 v224, v235
	v_pk_mul_f32 v[116:117], v[116:117], v[224:225] op_sel_hi:[1,0]
	v_pk_mul_f32 v[118:119], v[118:119], v[224:225] op_sel_hi:[1,0]
	v_pk_mul_f32 v[112:113], v[112:113], v[224:225] op_sel_hi:[1,0]
	v_pk_mul_f32 v[114:115], v[114:115], v[224:225] op_sel_hi:[1,0]
	v_exp_f32_e32 v116, v116
	v_exp_f32_e32 v117, v117
	v_exp_f32_e32 v118, v118
	v_exp_f32_e32 v119, v119
	v_exp_f32_e32 v112, v112
	v_exp_f32_e32 v113, v113
	v_exp_f32_e32 v114, v114
	v_exp_f32_e32 v115, v115
	v_pk_add_f32 v[116:117], v[116:117], 1.0 op_sel_hi:[1,0]
	v_pk_add_f32 v[118:119], v[118:119], 1.0 op_sel_hi:[1,0]
	v_pk_add_f32 v[112:113], v[112:113], 1.0 op_sel_hi:[1,0]
	v_pk_add_f32 v[114:115], v[114:115], 1.0 op_sel_hi:[1,0]
	v_rcp_f32_e32 v116, v116
	v_rcp_f32_e32 v117, v117
	v_rcp_f32_e32 v118, v118
	v_rcp_f32_e32 v119, v119
	v_rcp_f32_e32 v112, v112
	v_rcp_f32_e32 v113, v113
	v_rcp_f32_e32 v114, v114
	v_rcp_f32_e32 v115, v115
	v_lshlrev_b32_e32 v245, 1, v219
	s_waitcnt vmcnt(16)
	v_lshlrev_b32_e32 v220, 16, v168
	v_and_b32_e32 v221, 0xffff0000, v168
	v_lshlrev_b32_e32 v222, 16, v172
	v_and_b32_e32 v223, 0xffff0000, v172
	v_pk_fma_f32 v[116:117], v[116:117], v[222:223], v[220:221]
	v_lshlrev_b32_e32 v220, 16, v169
	v_and_b32_e32 v221, 0xffff0000, v169
	v_lshlrev_b32_e32 v222, 16, v173
	v_and_b32_e32 v223, 0xffff0000, v173
	v_pk_fma_f32 v[118:119], v[118:119], v[222:223], v[220:221]
	v_lshlrev_b32_e32 v220, 16, v170
	v_and_b32_e32 v221, 0xffff0000, v170
	v_lshlrev_b32_e32 v222, 16, v174
	v_and_b32_e32 v223, 0xffff0000, v174
	v_pk_fma_f32 v[112:113], v[112:113], v[222:223], v[220:221]
	v_lshlrev_b32_e32 v220, 16, v171
	v_and_b32_e32 v221, 0xffff0000, v171
	v_lshlrev_b32_e32 v222, 16, v175
	v_and_b32_e32 v223, 0xffff0000, v175
	v_pk_fma_f32 v[114:115], v[114:115], v[222:223], v[220:221]
	global_store_dwordx4 v245, v[116:119], s[24:25] offset:512
	global_store_dwordx4 v245, v[112:115], s[24:25] offset:528
	global_load_dwordx4 v[168:171], v231, s[34:35] offset:256
	global_load_dwordx4 v[172:175], v231, s[46:47] offset:256
	v_mov_b32_e32 v224, v236
	v_pk_mul_f32 v[108:109], v[108:109], v[224:225] op_sel_hi:[1,0]
	v_pk_mul_f32 v[110:111], v[110:111], v[224:225] op_sel_hi:[1,0]
	v_pk_mul_f32 v[104:105], v[104:105], v[224:225] op_sel_hi:[1,0]
	v_pk_mul_f32 v[106:107], v[106:107], v[224:225] op_sel_hi:[1,0]
	v_exp_f32_e32 v108, v108
	v_exp_f32_e32 v109, v109
	v_exp_f32_e32 v110, v110
	v_exp_f32_e32 v111, v111
	v_exp_f32_e32 v104, v104
	v_exp_f32_e32 v105, v105
	v_exp_f32_e32 v106, v106
	v_exp_f32_e32 v107, v107
	v_pk_add_f32 v[108:109], v[108:109], 1.0 op_sel_hi:[1,0]
	v_pk_add_f32 v[110:111], v[110:111], 1.0 op_sel_hi:[1,0]
	v_pk_add_f32 v[104:105], v[104:105], 1.0 op_sel_hi:[1,0]
	v_pk_add_f32 v[106:107], v[106:107], 1.0 op_sel_hi:[1,0]
	v_rcp_f32_e32 v108, v108
	v_rcp_f32_e32 v109, v109
	v_rcp_f32_e32 v110, v110
	v_rcp_f32_e32 v111, v111
	v_rcp_f32_e32 v104, v104
	v_rcp_f32_e32 v105, v105
	v_rcp_f32_e32 v106, v106
	v_rcp_f32_e32 v107, v107
	v_lshlrev_b32_e32 v245, 1, v228
	s_waitcnt vmcnt(18)
	v_lshlrev_b32_e32 v220, 16, v196
	v_and_b32_e32 v221, 0xffff0000, v196
	v_lshlrev_b32_e32 v222, 16, v200
	v_and_b32_e32 v223, 0xffff0000, v200
	v_pk_fma_f32 v[108:109], v[108:109], v[222:223], v[220:221]
	v_lshlrev_b32_e32 v220, 16, v197
	v_and_b32_e32 v221, 0xffff0000, v197
	v_lshlrev_b32_e32 v222, 16, v201
	v_and_b32_e32 v223, 0xffff0000, v201
	v_pk_fma_f32 v[110:111], v[110:111], v[222:223], v[220:221]
	v_lshlrev_b32_e32 v220, 16, v198
	v_and_b32_e32 v221, 0xffff0000, v198
	v_lshlrev_b32_e32 v222, 16, v202
	v_and_b32_e32 v223, 0xffff0000, v202
	v_pk_fma_f32 v[104:105], v[104:105], v[222:223], v[220:221]
	v_lshlrev_b32_e32 v220, 16, v199
	v_and_b32_e32 v221, 0xffff0000, v199
	v_lshlrev_b32_e32 v222, 16, v203
	v_and_b32_e32 v223, 0xffff0000, v203
	v_pk_fma_f32 v[106:107], v[106:107], v[222:223], v[220:221]
	global_store_dwordx4 v245, v[108:111], s[24:25]
	global_store_dwordx4 v245, v[104:107], s[24:25] offset:16
	global_load_dwordx4 v[196:199], v232, s[34:35]
	global_load_dwordx4 v[200:203], v232, s[46:47]
	v_mov_b32_e32 v224, v236
	v_pk_mul_f32 v[100:101], v[100:101], v[224:225] op_sel_hi:[1,0]
	v_pk_mul_f32 v[102:103], v[102:103], v[224:225] op_sel_hi:[1,0]
	v_pk_mul_f32 v[96:97], v[96:97], v[224:225] op_sel_hi:[1,0]
	v_pk_mul_f32 v[98:99], v[98:99], v[224:225] op_sel_hi:[1,0]
	v_exp_f32_e32 v100, v100
	v_exp_f32_e32 v101, v101
	v_exp_f32_e32 v102, v102
	v_exp_f32_e32 v103, v103
	v_exp_f32_e32 v96, v96
	v_exp_f32_e32 v97, v97
	v_exp_f32_e32 v98, v98
	v_exp_f32_e32 v99, v99
	v_pk_add_f32 v[100:101], v[100:101], 1.0 op_sel_hi:[1,0]
	v_pk_add_f32 v[102:103], v[102:103], 1.0 op_sel_hi:[1,0]
	v_pk_add_f32 v[96:97], v[96:97], 1.0 op_sel_hi:[1,0]
	v_pk_add_f32 v[98:99], v[98:99], 1.0 op_sel_hi:[1,0]
	v_rcp_f32_e32 v100, v100
	v_rcp_f32_e32 v101, v101
	v_rcp_f32_e32 v102, v102
	v_rcp_f32_e32 v103, v103
	v_rcp_f32_e32 v96, v96
	v_rcp_f32_e32 v97, v97
	v_rcp_f32_e32 v98, v98
	v_rcp_f32_e32 v99, v99
	v_lshlrev_b32_e32 v245, 1, v228
	s_waitcnt vmcnt(20)
; __device__ __forceinline__ float fast_rcp(float x) { return __builtin_amdgcn_rcpf(x); }
;     __device__ __forceinline__ void operator()(const f32x4 (&acc)[2][2][4][2], const Unit& u, int wr, int wc, int fr, int fq) const {
;     ...
;                 for (int mm = 0; mm < 2; ++mm) {
;                     const int m = 2 * mp + mm; const int r = row0 + ai * HALF + m * 16; const float nrs = rsv[ai][m] * -1.4426950408889634f;
; #pragma unroll
;                     for (int bj = 0; bj < 2; ++bj) {
;                         const size_t off = (size_t)r * 1024 + col0 + bj * HALF;
;                         const unsigned xw[4] = {xr[mm][bj].x, xr[mm][bj].y, xr[mm][bj].z, xr[mm][bj].w}, pw[4] = {pr[mm][bj].x, pr[mm][bj].y, pr[mm][bj].z, pr[mm][bj].w};
;                         f32x4 o[2];
; #pragma unroll
;                         for (int q = 0; q < 4; ++q) {
;                             const float t0 = acc[ai][bj][m][q >> 1][2 * (q & 1)] * nrs, t1 = acc[ai][bj][m][q >> 1][2 * (q & 1) + 1] * nrs;
;                             o[q >> 1][2 * (q & 1)] = __uint_as_float(xw[q] << 16) + fast_rcp(1.0f + __builtin_amdgcn_exp2f(t0)) * __uint_as_float(pw[q] << 16);
;                             o[q >> 1][2 * (q & 1) + 1] = __uint_as_float(xw[q] & 0xffff0000u) + fast_rcp(1.0f + __builtin_amdgcn_exp2f(t1)) * __uint_as_float(pw[q] & 0xffff0000u);
;                         }
;                         *(f32x4*)(Y + off) = o[0]; *(f32x4*)(Y + off + 4) = o[1];
	v_lshlrev_b32_e32 v220, 16, v204
	v_and_b32_e32 v221, 0xffff0000, v204
	v_lshlrev_b32_e32 v222, 16, v208
	v_and_b32_e32 v223, 0xffff0000, v208
	v_pk_fma_f32 v[100:101], v[100:101], v[222:223], v[220:221]
	v_lshlrev_b32_e32 v220, 16, v205
	v_and_b32_e32 v221, 0xffff0000, v205
	v_lshlrev_b32_e32 v222, 16, v209
	v_and_b32_e32 v223, 0xffff0000, v209
	v_pk_fma_f32 v[102:103], v[102:103], v[222:223], v[220:221]
	v_lshlrev_b32_e32 v220, 16, v206
	v_and_b32_e32 v221, 0xffff0000, v206
	v_lshlrev_b32_e32 v222, 16, v210
	v_and_b32_e32 v223, 0xffff0000, v210
	v_pk_fma_f32 v[96:97], v[96:97], v[222:223], v[220:221]
	v_lshlrev_b32_e32 v220, 16, v207
	v_and_b32_e32 v221, 0xffff0000, v207
	v_lshlrev_b32_e32 v222, 16, v211
	v_and_b32_e32 v223, 0xffff0000, v211
	v_pk_fma_f32 v[98:99], v[98:99], v[222:223], v[220:221]
	global_store_dwordx4 v245, v[100:103], s[24:25] offset:512
	global_store_dwordx4 v245, v[96:99], s[24:25] offset:528
	global_load_dwordx4 v[204:207], v232, s[34:35] offset:256
	global_load_dwordx4 v[208:211], v232, s[46:47] offset:256
	v_mov_b32_e32 v224, v237
	v_pk_mul_f32 v[92:93], v[92:93], v[224:225] op_sel_hi:[1,0]
	v_pk_mul_f32 v[94:95], v[94:95], v[224:225] op_sel_hi:[1,0]
	v_pk_mul_f32 v[88:89], v[88:89], v[224:225] op_sel_hi:[1,0]
	v_pk_mul_f32 v[90:91], v[90:91], v[224:225] op_sel_hi:[1,0]
	v_exp_f32_e32 v92, v92
	v_exp_f32_e32 v93, v93
	v_exp_f32_e32 v94, v94
	v_exp_f32_e32 v95, v95
	v_exp_f32_e32 v88, v88
	v_exp_f32_e32 v89, v89
	v_exp_f32_e32 v90, v90
	v_exp_f32_e32 v91, v91
	v_pk_add_f32 v[92:93], v[92:93], 1.0 op_sel_hi:[1,0]
	v_pk_add_f32 v[94:95], v[94:95], 1.0 op_sel_hi:[1,0]
	v_pk_add_f32 v[88:89], v[88:89], 1.0 op_sel_hi:[1,0]
	v_pk_add_f32 v[90:91], v[90:91], 1.0 op_sel_hi:[1,0]
	v_rcp_f32_e32 v92, v92
	v_rcp_f32_e32 v93, v93
	v_rcp_f32_e32 v94, v94
	v_rcp_f32_e32 v95, v95
	v_rcp_f32_e32 v88, v88
	v_rcp_f32_e32 v89, v89
	v_rcp_f32_e32 v90, v90
	v_rcp_f32_e32 v91, v91
	v_lshlrev_b32_e32 v245, 1, v229
	s_waitcnt vmcnt(22)
	v_lshlrev_b32_e32 v220, 16, v124
	v_and_b32_e32 v221, 0xffff0000, v124
	v_lshlrev_b32_e32 v222, 16, v132
	v_and_b32_e32 v223, 0xffff0000, v132
	v_pk_fma_f32 v[92:93], v[92:93], v[222:223], v[220:221]
	v_lshlrev_b32_e32 v220, 16, v125
	v_and_b32_e32 v221, 0xffff0000, v125
	v_lshlrev_b32_e32 v222, 16, v133
	v_and_b32_e32 v223, 0xffff0000, v133
	v_pk_fma_f32 v[94:95], v[94:95], v[222:223], v[220:221]
	v_lshlrev_b32_e32 v220, 16, v126
	v_and_b32_e32 v221, 0xffff0000, v126
	v_lshlrev_b32_e32 v222, 16, v134
	v_and_b32_e32 v223, 0xffff0000, v134
	v_pk_fma_f32 v[88:89], v[88:89], v[222:223], v[220:221]
	v_lshlrev_b32_e32 v220, 16, v127
	v_and_b32_e32 v221, 0xffff0000, v127
	v_lshlrev_b32_e32 v222, 16, v135
	v_and_b32_e32 v223, 0xffff0000, v135
	v_pk_fma_f32 v[90:91], v[90:91], v[222:223], v[220:221]
	global_store_dwordx4 v245, v[92:95], s[24:25]
	global_store_dwordx4 v245, v[88:91], s[24:25] offset:16
	global_load_dwordx4 v[124:127], v233, s[34:35]
	global_load_dwordx4 v[132:135], v233, s[46:47]
	v_mov_b32_e32 v224, v237
	v_pk_mul_f32 v[84:85], v[84:85], v[224:225] op_sel_hi:[1,0]
	v_pk_mul_f32 v[86:87], v[86:87], v[224:225] op_sel_hi:[1,0]
	v_pk_mul_f32 v[80:81], v[80:81], v[224:225] op_sel_hi:[1,0]
	v_pk_mul_f32 v[82:83], v[82:83], v[224:225] op_sel_hi:[1,0]
	v_exp_f32_e32 v84, v84
	v_exp_f32_e32 v85, v85
	v_exp_f32_e32 v86, v86
	v_exp_f32_e32 v87, v87
	v_exp_f32_e32 v80, v80
	v_exp_f32_e32 v81, v81
	v_exp_f32_e32 v82, v82
	v_exp_f32_e32 v83, v83
	v_pk_add_f32 v[84:85], v[84:85], 1.0 op_sel_hi:[1,0]
	v_pk_add_f32 v[86:87], v[86:87], 1.0 op_sel_hi:[1,0]
	v_pk_add_f32 v[80:81], v[80:81], 1.0 op_sel_hi:[1,0]
	v_pk_add_f32 v[82:83], v[82:83], 1.0 op_sel_hi:[1,0]
	v_rcp_f32_e32 v84, v84
	v_rcp_f32_e32 v85, v85
	v_rcp_f32_e32 v86, v86
	v_rcp_f32_e32 v87, v87
	v_rcp_f32_e32 v80, v80
	v_rcp_f32_e32 v81, v81
	v_rcp_f32_e32 v82, v82
	v_rcp_f32_e32 v83, v83
	v_lshlrev_b32_e32 v245, 1, v229
	s_waitcnt vmcnt(24)
	v_lshlrev_b32_e32 v220, 16, v136
	v_and_b32_e32 v221, 0xffff0000, v136
	v_lshlrev_b32_e32 v222, 16, v140
	v_and_b32_e32 v223, 0xffff0000, v140
	v_pk_fma_f32 v[84:85], v[84:85], v[222:223], v[220:221]
	v_lshlrev_b32_e32 v220, 16, v137
	v_and_b32_e32 v221, 0xffff0000, v137
	v_lshlrev_b32_e32 v222, 16, v141
	v_and_b32_e32 v223, 0xffff0000, v141
	v_pk_fma_f32 v[86:87], v[86:87], v[222:223], v[220:221]
	v_lshlrev_b32_e32 v220, 16, v138
	v_and_b32_e32 v221, 0xffff0000, v138
	v_lshlrev_b32_e32 v222, 16, v142
	v_and_b32_e32 v223, 0xffff0000, v142
	v_pk_fma_f32 v[80:81], v[80:81], v[222:223], v[220:221]
	v_lshlrev_b32_e32 v220, 16, v139
	v_and_b32_e32 v221, 0xffff0000, v139
	v_lshlrev_b32_e32 v222, 16, v143
	v_and_b32_e32 v223, 0xffff0000, v143
	v_pk_fma_f32 v[82:83], v[82:83], v[222:223], v[220:221]
	global_store_dwordx4 v245, v[84:87], s[24:25] offset:512
	global_store_dwordx4 v245, v[80:83], s[24:25] offset:528
	global_load_dwordx4 v[136:139], v233, s[34:35] offset:256
	global_load_dwordx4 v[140:143], v233, s[46:47] offset:256
	v_mov_b32_e32 v224, v238
	v_pk_mul_f32 v[76:77], v[76:77], v[224:225] op_sel_hi:[1,0]
	v_pk_mul_f32 v[78:79], v[78:79], v[224:225] op_sel_hi:[1,0]
	v_pk_mul_f32 v[72:73], v[72:73], v[224:225] op_sel_hi:[1,0]
	v_pk_mul_f32 v[74:75], v[74:75], v[224:225] op_sel_hi:[1,0]
	v_exp_f32_e32 v76, v76
	v_exp_f32_e32 v77, v77
	v_exp_f32_e32 v78, v78
	v_exp_f32_e32 v79, v79
	v_exp_f32_e32 v72, v72
	v_exp_f32_e32 v73, v73
	v_exp_f32_e32 v74, v74
	v_exp_f32_e32 v75, v75
	v_pk_add_f32 v[76:77], v[76:77], 1.0 op_sel_hi:[1,0]
	v_pk_add_f32 v[78:79], v[78:79], 1.0 op_sel_hi:[1,0]
	v_pk_add_f32 v[72:73], v[72:73], 1.0 op_sel_hi:[1,0]
	v_pk_add_f32 v[74:75], v[74:75], 1.0 op_sel_hi:[1,0]
	v_rcp_f32_e32 v76, v76
	v_rcp_f32_e32 v77, v77
	v_rcp_f32_e32 v78, v78
	v_rcp_f32_e32 v79, v79
	v_rcp_f32_e32 v72, v72
	v_rcp_f32_e32 v73, v73
	v_rcp_f32_e32 v74, v74
	v_rcp_f32_e32 v75, v75
	v_lshlrev_b32_e32 v245, 1, v230
	s_waitcnt vmcnt(26)
; __device__ __forceinline__ float fast_rcp(float x) { return __builtin_amdgcn_rcpf(x); }
;     __device__ __forceinline__ void operator()(const f32x4 (&acc)[2][2][4][2], const Unit& u, int wr, int wc, int fr, int fq) const {
;     ...
;                 for (int mm = 0; mm < 2; ++mm) {
;                     const int m = 2 * mp + mm; const int r = row0 + ai * HALF + m * 16; const float nrs = rsv[ai][m] * -1.4426950408889634f;
; #pragma unroll
;                     for (int bj = 0; bj < 2; ++bj) {
;                         const size_t off = (size_t)r * 1024 + col0 + bj * HALF;
;                         const unsigned xw[4] = {xr[mm][bj].x, xr[mm][bj].y, xr[mm][bj].z, xr[mm][bj].w}, pw[4] = {pr[mm][bj].x, pr[mm][bj].y, pr[mm][bj].z, pr[mm][bj].w};
;                         f32x4 o[2];
; #pragma unroll
;                         for (int q = 0; q < 4; ++q) {
;                             const float t0 = acc[ai][bj][m][q >> 1][2 * (q & 1)] * nrs, t1 = acc[ai][bj][m][q >> 1][2 * (q & 1) + 1] * nrs;
;                             o[q >> 1][2 * (q & 1)] = __uint_as_float(xw[q] << 16) + fast_rcp(1.0f + __builtin_amdgcn_exp2f(t0)) * __uint_as_float(pw[q] << 16);
;                             o[q >> 1][2 * (q & 1) + 1] = __uint_as_float(xw[q] & 0xffff0000u) + fast_rcp(1.0f + __builtin_amdgcn_exp2f(t1)) * __uint_as_float(pw[q] & 0xffff0000u);
;                         }
;                         *(f32x4*)(Y + off) = o[0]; *(f32x4*)(Y + off + 4) = o[1];
	v_lshlrev_b32_e32 v220, 16, v144
	v_and_b32_e32 v221, 0xffff0000, v144
	v_lshlrev_b32_e32 v222, 16, v148
	v_and_b32_e32 v223, 0xffff0000, v148
	v_pk_fma_f32 v[76:77], v[76:77], v[222:223], v[220:221]
	v_lshlrev_b32_e32 v220, 16, v145
	v_and_b32_e32 v221, 0xffff0000, v145
	v_lshlrev_b32_e32 v222, 16, v149
	v_and_b32_e32 v223, 0xffff0000, v149
	v_pk_fma_f32 v[78:79], v[78:79], v[222:223], v[220:221]
	v_lshlrev_b32_e32 v220, 16, v146
	v_and_b32_e32 v221, 0xffff0000, v146
	v_lshlrev_b32_e32 v222, 16, v150
	v_and_b32_e32 v223, 0xffff0000, v150
	v_pk_fma_f32 v[72:73], v[72:73], v[222:223], v[220:221]
	v_lshlrev_b32_e32 v220, 16, v147
	v_and_b32_e32 v221, 0xffff0000, v147
	v_lshlrev_b32_e32 v222, 16, v151
	v_and_b32_e32 v223, 0xffff0000, v151
	v_pk_fma_f32 v[74:75], v[74:75], v[222:223], v[220:221]
	global_store_dwordx4 v245, v[76:79], s[24:25]
	global_store_dwordx4 v245, v[72:75], s[24:25] offset:16
	global_load_dwordx4 v[144:147], v234, s[34:35]
	global_load_dwordx4 v[148:151], v234, s[46:47]
	v_mov_b32_e32 v224, v238
	v_pk_mul_f32 v[68:69], v[68:69], v[224:225] op_sel_hi:[1,0]
	v_pk_mul_f32 v[70:71], v[70:71], v[224:225] op_sel_hi:[1,0]
	v_pk_mul_f32 v[64:65], v[64:65], v[224:225] op_sel_hi:[1,0]
	v_pk_mul_f32 v[66:67], v[66:67], v[224:225] op_sel_hi:[1,0]
	v_exp_f32_e32 v68, v68
	v_exp_f32_e32 v69, v69
	v_exp_f32_e32 v70, v70
	v_exp_f32_e32 v71, v71
	v_exp_f32_e32 v64, v64
	v_exp_f32_e32 v65, v65
	v_exp_f32_e32 v66, v66
	v_exp_f32_e32 v67, v67
	v_pk_add_f32 v[68:69], v[68:69], 1.0 op_sel_hi:[1,0]
	v_pk_add_f32 v[70:71], v[70:71], 1.0 op_sel_hi:[1,0]
	v_pk_add_f32 v[64:65], v[64:65], 1.0 op_sel_hi:[1,0]
	v_pk_add_f32 v[66:67], v[66:67], 1.0 op_sel_hi:[1,0]
	v_rcp_f32_e32 v68, v68
	v_rcp_f32_e32 v69, v69
	v_rcp_f32_e32 v70, v70
	v_rcp_f32_e32 v71, v71
	v_rcp_f32_e32 v64, v64
	v_rcp_f32_e32 v65, v65
	v_rcp_f32_e32 v66, v66
	v_rcp_f32_e32 v67, v67
	v_lshlrev_b32_e32 v245, 1, v230
	s_waitcnt vmcnt(28)
	v_lshlrev_b32_e32 v220, 16, v152
	v_and_b32_e32 v221, 0xffff0000, v152
	v_lshlrev_b32_e32 v222, 16, v156
	v_and_b32_e32 v223, 0xffff0000, v156
	v_pk_fma_f32 v[68:69], v[68:69], v[222:223], v[220:221]
	v_lshlrev_b32_e32 v220, 16, v153
	v_and_b32_e32 v221, 0xffff0000, v153
	v_lshlrev_b32_e32 v222, 16, v157
	v_and_b32_e32 v223, 0xffff0000, v157
	v_pk_fma_f32 v[70:71], v[70:71], v[222:223], v[220:221]
	v_lshlrev_b32_e32 v220, 16, v154
	v_and_b32_e32 v221, 0xffff0000, v154
	v_lshlrev_b32_e32 v222, 16, v158
	v_and_b32_e32 v223, 0xffff0000, v158
	v_pk_fma_f32 v[64:65], v[64:65], v[222:223], v[220:221]
	v_lshlrev_b32_e32 v220, 16, v155
	v_and_b32_e32 v221, 0xffff0000, v155
	v_lshlrev_b32_e32 v222, 16, v159
	v_and_b32_e32 v223, 0xffff0000, v159
	v_pk_fma_f32 v[66:67], v[66:67], v[222:223], v[220:221]
	global_store_dwordx4 v245, v[68:71], s[24:25] offset:512
	global_store_dwordx4 v245, v[64:67], s[24:25] offset:528
	global_load_dwordx4 v[152:155], v234, s[34:35] offset:256
	global_load_dwordx4 v[156:159], v234, s[46:47] offset:256
	v_mov_b32_e32 v224, v239
	v_pk_mul_f32 v[60:61], v[60:61], v[224:225] op_sel_hi:[1,0]
	v_pk_mul_f32 v[62:63], v[62:63], v[224:225] op_sel_hi:[1,0]
	v_pk_mul_f32 v[56:57], v[56:57], v[224:225] op_sel_hi:[1,0]
	v_pk_mul_f32 v[58:59], v[58:59], v[224:225] op_sel_hi:[1,0]
	v_exp_f32_e32 v60, v60
	v_exp_f32_e32 v61, v61
	v_exp_f32_e32 v62, v62
	v_exp_f32_e32 v63, v63
	v_exp_f32_e32 v56, v56
	v_exp_f32_e32 v57, v57
	v_exp_f32_e32 v58, v58
	v_exp_f32_e32 v59, v59
	v_pk_add_f32 v[60:61], v[60:61], 1.0 op_sel_hi:[1,0]
	v_pk_add_f32 v[62:63], v[62:63], 1.0 op_sel_hi:[1,0]
	v_pk_add_f32 v[56:57], v[56:57], 1.0 op_sel_hi:[1,0]
	v_pk_add_f32 v[58:59], v[58:59], 1.0 op_sel_hi:[1,0]
	v_rcp_f32_e32 v60, v60
	v_rcp_f32_e32 v61, v61
	v_rcp_f32_e32 v62, v62
	v_rcp_f32_e32 v63, v63
	v_rcp_f32_e32 v56, v56
	v_rcp_f32_e32 v57, v57
	v_rcp_f32_e32 v58, v58
	v_rcp_f32_e32 v59, v59
	v_lshlrev_b32_e32 v245, 1, v231
	s_waitcnt vmcnt(28)
	v_lshlrev_b32_e32 v220, 16, v160
	v_and_b32_e32 v221, 0xffff0000, v160
	v_lshlrev_b32_e32 v222, 16, v164
	v_and_b32_e32 v223, 0xffff0000, v164
	v_pk_fma_f32 v[60:61], v[60:61], v[222:223], v[220:221]
	v_lshlrev_b32_e32 v220, 16, v161
	v_and_b32_e32 v221, 0xffff0000, v161
	v_lshlrev_b32_e32 v222, 16, v165
	v_and_b32_e32 v223, 0xffff0000, v165
	v_pk_fma_f32 v[62:63], v[62:63], v[222:223], v[220:221]
	v_lshlrev_b32_e32 v220, 16, v162
	v_and_b32_e32 v221, 0xffff0000, v162
	v_lshlrev_b32_e32 v222, 16, v166
	v_and_b32_e32 v223, 0xffff0000, v166
	v_pk_fma_f32 v[56:57], v[56:57], v[222:223], v[220:221]
	v_lshlrev_b32_e32 v220, 16, v163
	v_and_b32_e32 v221, 0xffff0000, v163
	v_lshlrev_b32_e32 v222, 16, v167
	v_and_b32_e32 v223, 0xffff0000, v167
	v_pk_fma_f32 v[58:59], v[58:59], v[222:223], v[220:221]
	global_store_dwordx4 v245, v[60:63], s[24:25]
	global_store_dwordx4 v245, v[56:59], s[24:25] offset:16
	v_mov_b32_e32 v224, v239
	v_pk_mul_f32 v[52:53], v[52:53], v[224:225] op_sel_hi:[1,0]
	v_pk_mul_f32 v[54:55], v[54:55], v[224:225] op_sel_hi:[1,0]
	v_pk_mul_f32 v[48:49], v[48:49], v[224:225] op_sel_hi:[1,0]
	v_pk_mul_f32 v[50:51], v[50:51], v[224:225] op_sel_hi:[1,0]
	v_exp_f32_e32 v52, v52
	v_exp_f32_e32 v53, v53
	v_exp_f32_e32 v54, v54
	v_exp_f32_e32 v55, v55
	v_exp_f32_e32 v48, v48
	v_exp_f32_e32 v49, v49
	v_exp_f32_e32 v50, v50
	v_exp_f32_e32 v51, v51
	v_pk_add_f32 v[52:53], v[52:53], 1.0 op_sel_hi:[1,0]
	v_pk_add_f32 v[54:55], v[54:55], 1.0 op_sel_hi:[1,0]
	v_pk_add_f32 v[48:49], v[48:49], 1.0 op_sel_hi:[1,0]
	v_pk_add_f32 v[50:51], v[50:51], 1.0 op_sel_hi:[1,0]
	v_rcp_f32_e32 v52, v52
	v_rcp_f32_e32 v53, v53
	v_rcp_f32_e32 v54, v54
	v_rcp_f32_e32 v55, v55
	v_rcp_f32_e32 v48, v48
	v_rcp_f32_e32 v49, v49
	v_rcp_f32_e32 v50, v50
	v_rcp_f32_e32 v51, v51
	v_lshlrev_b32_e32 v245, 1, v231
	s_waitcnt vmcnt(26)
; __device__ __forceinline__ float fast_rcp(float x) { return __builtin_amdgcn_rcpf(x); }
;     __device__ __forceinline__ void operator()(const f32x4 (&acc)[2][2][4][2], const Unit& u, int wr, int wc, int fr, int fq) const {
;     ...
;                 for (int mm = 0; mm < 2; ++mm) {
;                     const int m = 2 * mp + mm; const int r = row0 + ai * HALF + m * 16; const float nrs = rsv[ai][m] * -1.4426950408889634f;
; #pragma unroll
;                     for (int bj = 0; bj < 2; ++bj) {
;                         const size_t off = (size_t)r * 1024 + col0 + bj * HALF;
;                         const unsigned xw[4] = {xr[mm][bj].x, xr[mm][bj].y, xr[mm][bj].z, xr[mm][bj].w}, pw[4] = {pr[mm][bj].x, pr[mm][bj].y, pr[mm][bj].z, pr[mm][bj].w};
;                         f32x4 o[2];
; #pragma unroll
;                         for (int q = 0; q < 4; ++q) {
;                             const float t0 = acc[ai][bj][m][q >> 1][2 * (q & 1)] * nrs, t1 = acc[ai][bj][m][q >> 1][2 * (q & 1) + 1] * nrs;
;                             o[q >> 1][2 * (q & 1)] = __uint_as_float(xw[q] << 16) + fast_rcp(1.0f + __builtin_amdgcn_exp2f(t0)) * __uint_as_float(pw[q] << 16);
;                             o[q >> 1][2 * (q & 1) + 1] = __uint_as_float(xw[q] & 0xffff0000u) + fast_rcp(1.0f + __builtin_amdgcn_exp2f(t1)) * __uint_as_float(pw[q] & 0xffff0000u);
;                         }
;                         *(f32x4*)(Y + off) = o[0]; *(f32x4*)(Y + off + 4) = o[1];
	v_lshlrev_b32_e32 v220, 16, v168
	v_and_b32_e32 v221, 0xffff0000, v168
	v_lshlrev_b32_e32 v222, 16, v172
	v_and_b32_e32 v223, 0xffff0000, v172
	v_pk_fma_f32 v[52:53], v[52:53], v[222:223], v[220:221]
	v_lshlrev_b32_e32 v220, 16, v169
	v_and_b32_e32 v221, 0xffff0000, v169
	v_lshlrev_b32_e32 v222, 16, v173
	v_and_b32_e32 v223, 0xffff0000, v173
	v_pk_fma_f32 v[54:55], v[54:55], v[222:223], v[220:221]
	v_lshlrev_b32_e32 v220, 16, v170
	v_and_b32_e32 v221, 0xffff0000, v170
	v_lshlrev_b32_e32 v222, 16, v174
	v_and_b32_e32 v223, 0xffff0000, v174
	v_pk_fma_f32 v[48:49], v[48:49], v[222:223], v[220:221]
	v_lshlrev_b32_e32 v220, 16, v171
	v_and_b32_e32 v221, 0xffff0000, v171
	v_lshlrev_b32_e32 v222, 16, v175
	v_and_b32_e32 v223, 0xffff0000, v175
	v_pk_fma_f32 v[50:51], v[50:51], v[222:223], v[220:221]
	global_store_dwordx4 v245, v[52:55], s[24:25] offset:512
	global_store_dwordx4 v245, v[48:51], s[24:25] offset:528
	v_mov_b32_e32 v224, v240
	v_pk_mul_f32 v[44:45], v[44:45], v[224:225] op_sel_hi:[1,0]
	v_pk_mul_f32 v[46:47], v[46:47], v[224:225] op_sel_hi:[1,0]
	v_pk_mul_f32 v[40:41], v[40:41], v[224:225] op_sel_hi:[1,0]
	v_pk_mul_f32 v[42:43], v[42:43], v[224:225] op_sel_hi:[1,0]
	v_exp_f32_e32 v44, v44
	v_exp_f32_e32 v45, v45
	v_exp_f32_e32 v46, v46
	v_exp_f32_e32 v47, v47
	v_exp_f32_e32 v40, v40
	v_exp_f32_e32 v41, v41
	v_exp_f32_e32 v42, v42
	v_exp_f32_e32 v43, v43
	v_pk_add_f32 v[44:45], v[44:45], 1.0 op_sel_hi:[1,0]
	v_pk_add_f32 v[46:47], v[46:47], 1.0 op_sel_hi:[1,0]
	v_pk_add_f32 v[40:41], v[40:41], 1.0 op_sel_hi:[1,0]
	v_pk_add_f32 v[42:43], v[42:43], 1.0 op_sel_hi:[1,0]
	v_rcp_f32_e32 v44, v44
	v_rcp_f32_e32 v45, v45
	v_rcp_f32_e32 v46, v46
	v_rcp_f32_e32 v47, v47
	v_rcp_f32_e32 v40, v40
	v_rcp_f32_e32 v41, v41
	v_rcp_f32_e32 v42, v42
	v_rcp_f32_e32 v43, v43
	v_lshlrev_b32_e32 v245, 1, v232
	s_waitcnt vmcnt(24)
	v_lshlrev_b32_e32 v220, 16, v196
	v_and_b32_e32 v221, 0xffff0000, v196
	v_lshlrev_b32_e32 v222, 16, v200
	v_and_b32_e32 v223, 0xffff0000, v200
	v_pk_fma_f32 v[44:45], v[44:45], v[222:223], v[220:221]
	v_lshlrev_b32_e32 v220, 16, v197
	v_and_b32_e32 v221, 0xffff0000, v197
	v_lshlrev_b32_e32 v222, 16, v201
	v_and_b32_e32 v223, 0xffff0000, v201
	v_pk_fma_f32 v[46:47], v[46:47], v[222:223], v[220:221]
	v_lshlrev_b32_e32 v220, 16, v198
	v_and_b32_e32 v221, 0xffff0000, v198
	v_lshlrev_b32_e32 v222, 16, v202
	v_and_b32_e32 v223, 0xffff0000, v202
	v_pk_fma_f32 v[40:41], v[40:41], v[222:223], v[220:221]
	v_lshlrev_b32_e32 v220, 16, v199
	v_and_b32_e32 v221, 0xffff0000, v199
	v_lshlrev_b32_e32 v222, 16, v203
	v_and_b32_e32 v223, 0xffff0000, v203
	v_pk_fma_f32 v[42:43], v[42:43], v[222:223], v[220:221]
	global_store_dwordx4 v245, v[44:47], s[24:25]
	global_store_dwordx4 v245, v[40:43], s[24:25] offset:16
	v_mov_b32_e32 v224, v240
	v_pk_mul_f32 v[36:37], v[36:37], v[224:225] op_sel_hi:[1,0]
	v_pk_mul_f32 v[38:39], v[38:39], v[224:225] op_sel_hi:[1,0]
	v_pk_mul_f32 v[32:33], v[32:33], v[224:225] op_sel_hi:[1,0]
	v_pk_mul_f32 v[34:35], v[34:35], v[224:225] op_sel_hi:[1,0]
	v_exp_f32_e32 v36, v36
	v_exp_f32_e32 v37, v37
	v_exp_f32_e32 v38, v38
	v_exp_f32_e32 v39, v39
	v_exp_f32_e32 v32, v32
	v_exp_f32_e32 v33, v33
	v_exp_f32_e32 v34, v34
	v_exp_f32_e32 v35, v35
	v_pk_add_f32 v[36:37], v[36:37], 1.0 op_sel_hi:[1,0]
	v_pk_add_f32 v[38:39], v[38:39], 1.0 op_sel_hi:[1,0]
	v_pk_add_f32 v[32:33], v[32:33], 1.0 op_sel_hi:[1,0]
	v_pk_add_f32 v[34:35], v[34:35], 1.0 op_sel_hi:[1,0]
	v_rcp_f32_e32 v36, v36
	v_rcp_f32_e32 v37, v37
	v_rcp_f32_e32 v38, v38
	v_rcp_f32_e32 v39, v39
	v_rcp_f32_e32 v32, v32
	v_rcp_f32_e32 v33, v33
	v_rcp_f32_e32 v34, v34
	v_rcp_f32_e32 v35, v35
	v_lshlrev_b32_e32 v245, 1, v232
	s_waitcnt vmcnt(22)
	v_lshlrev_b32_e32 v220, 16, v204
	v_and_b32_e32 v221, 0xffff0000, v204
	v_lshlrev_b32_e32 v222, 16, v208
	v_and_b32_e32 v223, 0xffff0000, v208
	v_pk_fma_f32 v[36:37], v[36:37], v[222:223], v[220:221]
	v_lshlrev_b32_e32 v220, 16, v205
	v_and_b32_e32 v221, 0xffff0000, v205
	v_lshlrev_b32_e32 v222, 16, v209
	v_and_b32_e32 v223, 0xffff0000, v209
	v_pk_fma_f32 v[38:39], v[38:39], v[222:223], v[220:221]
	v_lshlrev_b32_e32 v220, 16, v206
	v_and_b32_e32 v221, 0xffff0000, v206
	v_lshlrev_b32_e32 v222, 16, v210
	v_and_b32_e32 v223, 0xffff0000, v210
	v_pk_fma_f32 v[32:33], v[32:33], v[222:223], v[220:221]
	v_lshlrev_b32_e32 v220, 16, v207
	v_and_b32_e32 v221, 0xffff0000, v207
	v_lshlrev_b32_e32 v222, 16, v211
	v_and_b32_e32 v223, 0xffff0000, v211
	v_pk_fma_f32 v[34:35], v[34:35], v[222:223], v[220:221]
	global_store_dwordx4 v245, v[36:39], s[24:25] offset:512
	global_store_dwordx4 v245, v[32:35], s[24:25] offset:528
	v_mov_b32_e32 v224, v241
	v_pk_mul_f32 v[28:29], v[28:29], v[224:225] op_sel_hi:[1,0]
	v_pk_mul_f32 v[30:31], v[30:31], v[224:225] op_sel_hi:[1,0]
	v_pk_mul_f32 v[24:25], v[24:25], v[224:225] op_sel_hi:[1,0]
	v_pk_mul_f32 v[26:27], v[26:27], v[224:225] op_sel_hi:[1,0]
	v_exp_f32_e32 v28, v28
	v_exp_f32_e32 v29, v29
	v_exp_f32_e32 v30, v30
	v_exp_f32_e32 v31, v31
	v_exp_f32_e32 v24, v24
	v_exp_f32_e32 v25, v25
	v_exp_f32_e32 v26, v26
	v_exp_f32_e32 v27, v27
	v_pk_add_f32 v[28:29], v[28:29], 1.0 op_sel_hi:[1,0]
	v_pk_add_f32 v[30:31], v[30:31], 1.0 op_sel_hi:[1,0]
	v_pk_add_f32 v[24:25], v[24:25], 1.0 op_sel_hi:[1,0]
	v_pk_add_f32 v[26:27], v[26:27], 1.0 op_sel_hi:[1,0]
	v_rcp_f32_e32 v28, v28
	v_rcp_f32_e32 v29, v29
	v_rcp_f32_e32 v30, v30
	v_rcp_f32_e32 v31, v31
	v_rcp_f32_e32 v24, v24
	v_rcp_f32_e32 v25, v25
	v_rcp_f32_e32 v26, v26
	v_rcp_f32_e32 v27, v27
	v_lshlrev_b32_e32 v245, 1, v233
	s_waitcnt vmcnt(20)
; __device__ __forceinline__ float fast_rcp(float x) { return __builtin_amdgcn_rcpf(x); }
;     __device__ __forceinline__ void operator()(const f32x4 (&acc)[2][2][4][2], const Unit& u, int wr, int wc, int fr, int fq) const {
;     ...
;                 for (int mm = 0; mm < 2; ++mm) {
;                     const int m = 2 * mp + mm; const int r = row0 + ai * HALF + m * 16; const float nrs = rsv[ai][m] * -1.4426950408889634f;
; #pragma unroll
;                     for (int bj = 0; bj < 2; ++bj) {
;                         const size_t off = (size_t)r * 1024 + col0 + bj * HALF;
;                         const unsigned xw[4] = {xr[mm][bj].x, xr[mm][bj].y, xr[mm][bj].z, xr[mm][bj].w}, pw[4] = {pr[mm][bj].x, pr[mm][bj].y, pr[mm][bj].z, pr[mm][bj].w};
;                         f32x4 o[2];
; #pragma unroll
;                         for (int q = 0; q < 4; ++q) {
;                             const float t0 = acc[ai][bj][m][q >> 1][2 * (q & 1)] * nrs, t1 = acc[ai][bj][m][q >> 1][2 * (q & 1) + 1] * nrs;
;                             o[q >> 1][2 * (q & 1)] = __uint_as_float(xw[q] << 16) + fast_rcp(1.0f + __builtin_amdgcn_exp2f(t0)) * __uint_as_float(pw[q] << 16);
;                             o[q >> 1][2 * (q & 1) + 1] = __uint_as_float(xw[q] & 0xffff0000u) + fast_rcp(1.0f + __builtin_amdgcn_exp2f(t1)) * __uint_as_float(pw[q] & 0xffff0000u);
;                         }
;                         *(f32x4*)(Y + off) = o[0]; *(f32x4*)(Y + off + 4) = o[1];
	v_lshlrev_b32_e32 v220, 16, v124
	v_and_b32_e32 v221, 0xffff0000, v124
	v_lshlrev_b32_e32 v222, 16, v132
	v_and_b32_e32 v223, 0xffff0000, v132
	v_pk_fma_f32 v[28:29], v[28:29], v[222:223], v[220:221]
	v_lshlrev_b32_e32 v220, 16, v125
	v_and_b32_e32 v221, 0xffff0000, v125
	v_lshlrev_b32_e32 v222, 16, v133
	v_and_b32_e32 v223, 0xffff0000, v133
	v_pk_fma_f32 v[30:31], v[30:31], v[222:223], v[220:221]
	v_lshlrev_b32_e32 v220, 16, v126
	v_and_b32_e32 v221, 0xffff0000, v126
	v_lshlrev_b32_e32 v222, 16, v134
	v_and_b32_e32 v223, 0xffff0000, v134
	v_pk_fma_f32 v[24:25], v[24:25], v[222:223], v[220:221]
	v_lshlrev_b32_e32 v220, 16, v127
	v_and_b32_e32 v221, 0xffff0000, v127
	v_lshlrev_b32_e32 v222, 16, v135
	v_and_b32_e32 v223, 0xffff0000, v135
	v_pk_fma_f32 v[26:27], v[26:27], v[222:223], v[220:221]
	global_store_dwordx4 v245, v[28:31], s[24:25]
	global_store_dwordx4 v245, v[24:27], s[24:25] offset:16
	v_mov_b32_e32 v224, v241
	v_pk_mul_f32 v[20:21], v[20:21], v[224:225] op_sel_hi:[1,0]
	v_pk_mul_f32 v[22:23], v[22:23], v[224:225] op_sel_hi:[1,0]
	v_pk_mul_f32 v[16:17], v[16:17], v[224:225] op_sel_hi:[1,0]
	v_pk_mul_f32 v[18:19], v[18:19], v[224:225] op_sel_hi:[1,0]
	v_exp_f32_e32 v20, v20
	v_exp_f32_e32 v21, v21
	v_exp_f32_e32 v22, v22
	v_exp_f32_e32 v23, v23
	v_exp_f32_e32 v16, v16
	v_exp_f32_e32 v17, v17
	v_exp_f32_e32 v18, v18
	v_exp_f32_e32 v19, v19
	v_pk_add_f32 v[20:21], v[20:21], 1.0 op_sel_hi:[1,0]
	v_pk_add_f32 v[22:23], v[22:23], 1.0 op_sel_hi:[1,0]
	v_pk_add_f32 v[16:17], v[16:17], 1.0 op_sel_hi:[1,0]
	v_pk_add_f32 v[18:19], v[18:19], 1.0 op_sel_hi:[1,0]
	v_rcp_f32_e32 v20, v20
	v_rcp_f32_e32 v21, v21
	v_rcp_f32_e32 v22, v22
	v_rcp_f32_e32 v23, v23
	v_rcp_f32_e32 v16, v16
	v_rcp_f32_e32 v17, v17
	v_rcp_f32_e32 v18, v18
	v_rcp_f32_e32 v19, v19
	v_lshlrev_b32_e32 v245, 1, v233
	s_waitcnt vmcnt(18)
	v_lshlrev_b32_e32 v220, 16, v136
	v_and_b32_e32 v221, 0xffff0000, v136
	v_lshlrev_b32_e32 v222, 16, v140
	v_and_b32_e32 v223, 0xffff0000, v140
	v_pk_fma_f32 v[20:21], v[20:21], v[222:223], v[220:221]
	v_lshlrev_b32_e32 v220, 16, v137
	v_and_b32_e32 v221, 0xffff0000, v137
	v_lshlrev_b32_e32 v222, 16, v141
	v_and_b32_e32 v223, 0xffff0000, v141
	v_pk_fma_f32 v[22:23], v[22:23], v[222:223], v[220:221]
	v_lshlrev_b32_e32 v220, 16, v138
	v_and_b32_e32 v221, 0xffff0000, v138
	v_lshlrev_b32_e32 v222, 16, v142
	v_and_b32_e32 v223, 0xffff0000, v142
	v_pk_fma_f32 v[16:17], v[16:17], v[222:223], v[220:221]
	v_lshlrev_b32_e32 v220, 16, v139
	v_and_b32_e32 v221, 0xffff0000, v139
	v_lshlrev_b32_e32 v222, 16, v143
	v_and_b32_e32 v223, 0xffff0000, v143
	v_pk_fma_f32 v[18:19], v[18:19], v[222:223], v[220:221]
	global_store_dwordx4 v245, v[20:23], s[24:25] offset:512
	global_store_dwordx4 v245, v[16:19], s[24:25] offset:528
	v_mov_b32_e32 v224, v242
	v_pk_mul_f32 v[12:13], v[12:13], v[224:225] op_sel_hi:[1,0]
	v_pk_mul_f32 v[14:15], v[14:15], v[224:225] op_sel_hi:[1,0]
	v_pk_mul_f32 v[8:9], v[8:9], v[224:225] op_sel_hi:[1,0]
	v_pk_mul_f32 v[10:11], v[10:11], v[224:225] op_sel_hi:[1,0]
	v_exp_f32_e32 v12, v12
	v_exp_f32_e32 v13, v13
	v_exp_f32_e32 v14, v14
	v_exp_f32_e32 v15, v15
	v_exp_f32_e32 v8, v8
	v_exp_f32_e32 v9, v9
	v_exp_f32_e32 v10, v10
	v_exp_f32_e32 v11, v11
	v_pk_add_f32 v[12:13], v[12:13], 1.0 op_sel_hi:[1,0]
	v_pk_add_f32 v[14:15], v[14:15], 1.0 op_sel_hi:[1,0]
	v_pk_add_f32 v[8:9], v[8:9], 1.0 op_sel_hi:[1,0]
	v_pk_add_f32 v[10:11], v[10:11], 1.0 op_sel_hi:[1,0]
	v_rcp_f32_e32 v12, v12
	v_rcp_f32_e32 v13, v13
	v_rcp_f32_e32 v14, v14
	v_rcp_f32_e32 v15, v15
	v_rcp_f32_e32 v8, v8
	v_rcp_f32_e32 v9, v9
	v_rcp_f32_e32 v10, v10
	v_rcp_f32_e32 v11, v11
	v_lshlrev_b32_e32 v245, 1, v234
	s_waitcnt vmcnt(16)
	v_lshlrev_b32_e32 v220, 16, v144
	v_and_b32_e32 v221, 0xffff0000, v144
	v_lshlrev_b32_e32 v222, 16, v148
	v_and_b32_e32 v223, 0xffff0000, v148
	v_pk_fma_f32 v[12:13], v[12:13], v[222:223], v[220:221]
	v_lshlrev_b32_e32 v220, 16, v145
	v_and_b32_e32 v221, 0xffff0000, v145
	v_lshlrev_b32_e32 v222, 16, v149
	v_and_b32_e32 v223, 0xffff0000, v149
	v_pk_fma_f32 v[14:15], v[14:15], v[222:223], v[220:221]
	v_lshlrev_b32_e32 v220, 16, v146
	v_and_b32_e32 v221, 0xffff0000, v146
	v_lshlrev_b32_e32 v222, 16, v150
	v_and_b32_e32 v223, 0xffff0000, v150
	v_pk_fma_f32 v[8:9], v[8:9], v[222:223], v[220:221]
	v_lshlrev_b32_e32 v220, 16, v147
	v_and_b32_e32 v221, 0xffff0000, v147
	v_lshlrev_b32_e32 v222, 16, v151
	v_and_b32_e32 v223, 0xffff0000, v151
	v_pk_fma_f32 v[10:11], v[10:11], v[222:223], v[220:221]
	global_store_dwordx4 v245, v[12:15], s[24:25]
	global_store_dwordx4 v245, v[8:11], s[24:25] offset:16
	v_mov_b32_e32 v224, v242
	v_pk_mul_f32 v[4:5], v[4:5], v[224:225] op_sel_hi:[1,0]
	v_pk_mul_f32 v[6:7], v[6:7], v[224:225] op_sel_hi:[1,0]
	v_pk_mul_f32 v[0:1], v[0:1], v[224:225] op_sel_hi:[1,0]
	v_pk_mul_f32 v[2:3], v[2:3], v[224:225] op_sel_hi:[1,0]
	v_exp_f32_e32 v4, v4
	v_exp_f32_e32 v5, v5
	v_exp_f32_e32 v6, v6
	v_exp_f32_e32 v7, v7
	v_exp_f32_e32 v0, v0
	v_exp_f32_e32 v1, v1
	v_exp_f32_e32 v2, v2
	v_exp_f32_e32 v3, v3
	v_pk_add_f32 v[4:5], v[4:5], 1.0 op_sel_hi:[1,0]
	v_pk_add_f32 v[6:7], v[6:7], 1.0 op_sel_hi:[1,0]
	v_pk_add_f32 v[0:1], v[0:1], 1.0 op_sel_hi:[1,0]
	v_pk_add_f32 v[2:3], v[2:3], 1.0 op_sel_hi:[1,0]
	v_rcp_f32_e32 v4, v4
	v_rcp_f32_e32 v5, v5
	v_rcp_f32_e32 v6, v6
	v_rcp_f32_e32 v7, v7
	v_rcp_f32_e32 v0, v0
	v_rcp_f32_e32 v1, v1
	v_rcp_f32_e32 v2, v2
	v_rcp_f32_e32 v3, v3
	v_lshlrev_b32_e32 v245, 1, v234
	s_waitcnt vmcnt(14)
	v_lshlrev_b32_e32 v220, 16, v152
	v_and_b32_e32 v221, 0xffff0000, v152
	v_lshlrev_b32_e32 v222, 16, v156
	v_and_b32_e32 v223, 0xffff0000, v156
	v_pk_fma_f32 v[4:5], v[4:5], v[222:223], v[220:221]
	v_lshlrev_b32_e32 v220, 16, v153
	v_and_b32_e32 v221, 0xffff0000, v153
	v_lshlrev_b32_e32 v222, 16, v157
	v_and_b32_e32 v223, 0xffff0000, v157
	v_pk_fma_f32 v[6:7], v[6:7], v[222:223], v[220:221]
	v_lshlrev_b32_e32 v220, 16, v154
	v_and_b32_e32 v221, 0xffff0000, v154
	v_lshlrev_b32_e32 v222, 16, v158
	v_and_b32_e32 v223, 0xffff0000, v158
	v_pk_fma_f32 v[0:1], v[0:1], v[222:223], v[220:221]
	v_lshlrev_b32_e32 v220, 16, v155
	v_and_b32_e32 v221, 0xffff0000, v155
	v_lshlrev_b32_e32 v222, 16, v159
	v_and_b32_e32 v223, 0xffff0000, v159
	v_pk_fma_f32 v[2:3], v[2:3], v[222:223], v[220:221]
	global_store_dwordx4 v245, v[4:7], s[24:25] offset:512
	global_store_dwordx4 v245, v[0:3], s[24:25] offset:528
	s_and_b64 vcc, exec, s[0:1]
	s_mov_b64 s[0:1], -1
	s_cbranch_vccnz .LBB0_1240
	s_andn2_b64 vcc, exec, s[12:13]
	s_cbranch_vccnz .LBB0_1239
	s_barrier
	s_branch .LBB0_1239
